# phase 0 load balance: the ninth row-conversion iteration moves from blocks 0-63 (which also run the sample-K items) to blocks 128-191
# speedup vs baseline: 1.0003x; 1.0003x over previous
.LBB0_82:
	s_add_u32 s0, s86, 0xf730000
	s_addc_u32 s1, s87, 0
	v_and_b32_e32 v22, 63, v1
	v_writelane_b32 v237, s0, 20
	s_cmpk_gt_i32 s2, 0x83f
	v_mbcnt_lo_u32_b32 v68, -1, 0
	v_writelane_b32 v237, s1, 21
	s_cbranch_scc1 .LBB0_95
	s_xor_b32 s99, s2, 0x80
	s_nop 0
	s_nop 0
	s_nop 0
	s_nop 0
	s_nop 0
	s_nop 0
	s_nop 0
	s_nop 0
	s_nop 0
	s_nop 0
	s_nop 0
	s_nop 0
	s_nop 0
	s_nop 0
	s_nop 0
	s_nop 0
	s_nop 0
	s_nop 0
	s_nop 0
	s_nop 0
	s_nop 0
	s_nop 0
	s_nop 0
	s_nop 0
	s_nop 0
	s_nop 0
	s_nop 0
	s_nop 0
	s_nop 0
	s_nop 0
	s_nop 0
	s_nop 0
	s_nop 0
	s_nop 0
	s_nop 0
	s_nop 0
	s_nop 0
	s_nop 0
	s_nop 0
	s_nop 0
	s_nop 0
	s_nop 0
	s_nop 0
	s_nop 0
	s_nop 0
	s_nop 0
	s_nop 0
	s_nop 0
	s_nop 0
	s_nop 0
	s_nop 0
	s_nop 0
	s_nop 0
	s_nop 0
	s_nop 0
	s_nop 0
	s_nop 0
	s_nop 0
	s_nop 0
	s_nop 0
	s_nop 0
	s_nop 0
	v_mbcnt_hi_u32_b32 v2, -1, v68
	v_and_b32_e32 v3, 64, v2
	v_add_u32_e32 v4, 64, v3
	v_xor_b32_e32 v5, 32, v2
	v_cmp_lt_i32_e32 vcc, v5, v4
	v_ashrrev_i32_e32 v6, 6, v1
	v_lshlrev_b32_e32 v8, 2, v22
	v_cndmask_b32_e32 v5, v2, v5, vcc
	v_lshlrev_b32_e32 v14, 2, v5
	v_xor_b32_e32 v5, 16, v2
	v_cmp_lt_i32_e32 vcc, v5, v4
	v_mov_b32_e32 v3, 0
	v_cmp_eq_u32_e64 s[0:1], 0, v22
	v_cndmask_b32_e32 v5, v2, v5, vcc
	v_lshlrev_b32_e32 v15, 2, v5
	v_xor_b32_e32 v5, 8, v2
	v_cmp_lt_i32_e32 vcc, v5, v4
	v_lshl_add_u32 v6, s99, 3, v6
	s_lshl_b32 s3, s8, 3
	v_cndmask_b32_e32 v5, v2, v5, vcc
	v_lshlrev_b32_e32 v16, 2, v5
	v_xor_b32_e32 v5, 4, v2
	v_cmp_lt_i32_e32 vcc, v5, v4
	s_movk_i32 s24, 0x3fff
	s_movk_i32 s25, 0x40ff
	v_cndmask_b32_e32 v5, v2, v5, vcc
	v_lshlrev_b32_e32 v17, 2, v5
	v_xor_b32_e32 v5, 2, v2
	v_cmp_lt_i32_e32 vcc, v5, v4
	v_lshlrev_b32_e32 v8, 2, v8
	v_mov_b32_e32 v9, v3
	v_cndmask_b32_e32 v5, v2, v5, vcc
	v_lshlrev_b32_e32 v18, 2, v5
	v_xor_b32_e32 v5, 1, v2
	v_cmp_lt_i32_e32 vcc, v5, v4
	v_mov_b32_e32 v20, 0x358637bd
	s_mov_b32 s26, s99
	v_cndmask_b32_e32 v2, v2, v5, vcc
	v_lshlrev_b32_e32 v19, 2, v2
	v_lshlrev_b32_e32 v2, 3, v22
	v_lshl_add_u64 v[4:5], s[84:85], 0, v[2:3]
	s_branch .LBB0_85
